# phase0 ffn_wup conversion items: dummy loads touch the next item's source lines (in-bounds by a scalar test) so its loads hit L2
# speedup vs baseline: 1.0002x; 1.0002x over previous
.LBB0_38:
	s_andn2_b64 vcc, exec, s[8:9]
	s_cbranch_vccnz .LBB0_40
	s_load_dwordx2 s[8:9], s[0:1], 0xb8
	s_add_i32 s14, s22, 0xfffffc88
	s_and_b64 s[10:11], s[12:13], exec
	s_cselect_b32 s10, 0x1600000, 0
	v_mov_b32_e32 v32, v190
	s_waitcnt lgkmcnt(0)
	s_add_u32 s8, s8, s10
	s_addc_u32 s9, s9, 0
	s_lshr_b32 s10, s14, 4
	s_lshl_b32 s11, s14, 6
	v_lshlrev_b32_e32 v0, 2, v32
	s_lshl_b32 s14, s10, 5
	v_and_b32_e32 v34, 60, v0
	s_add_i32 s20, s14, 0xb00
	s_and_b32 s11, s11, 0x3c0
	v_ashrrev_i32_e32 v33, 4, v32
	v_and_or_b32 v0, v0, 28, s20
	v_add_u32_e32 v1, s14, v34
	v_cmp_gt_u32_e32 vcc, 32, v34
	v_add_u32_e32 v22, s11, v33
	v_mov_b64_e32 v[4:5], s[8:9]
	v_cndmask_b32_e32 v18, v0, v1, vcc
	v_mad_i64_i32 v[0:1], s[8:9], v22, s38, v[4:5]
	v_lshlrev_b64 v[6:7], 2, v[18:19]
	v_lshl_add_u64 v[0:1], v[0:1], 0, v[6:7]
	v_add_u32_e32 v18, 32, v22
	s_cmpk_gt_u32 s22, 0x7f7
	s_cselect_b32 s74, 0, 0x800
	s_mov_b32 s75, 0
	v_lshl_add_u64 v[70:71], v[0:1], 0, s[74:75]
	global_load_dwordx4 v[0:3], v[0:1], off
	v_mad_i64_i32 v[4:5], s[8:9], v18, s38, v[4:5]
	v_lshl_add_u64 v[4:5], v[4:5], 0, v[6:7]
	v_lshl_add_u64 v[72:73], v[4:5], 0, s[74:75]
	global_load_dwordx4 v[4:7], v[4:5], off
	global_load_dword v74, v[70:71], off
	global_load_dword v74, v[72:73], off
	v_ashrrev_i32_e32 v18, 3, v32
	v_lshlrev_b32_e32 v32, 3, v32
	v_and_b32_e32 v32, 56, v32
	v_mul_lo_u32 v33, v33, s34
	v_lshlrev_b32_e32 v35, 2, v18
	v_lshlrev_b32_e32 v34, 2, v34
	v_mul_u32_u24_e32 v36, 0x104, v32
	v_add3_u32 v33, 0, v34, v33
	v_add3_u32 v34, 0, v36, v35
	v_add_u32_e32 v35, 0x5000, v33
	v_add_u32_e32 v38, 0x5000, v34
	v_mov_b64_e32 v[22:23], s[6:7]
	v_add_u32_e32 v36, 0x5008, v33
	v_add_u32_e32 v37, 0x7080, v33
	v_add_u32_e32 v33, 0x7088, v33
	v_add_u32_e32 v34, 0x5400, v34
	v_lshl_add_u32 v18, s10, 6, v18
	v_mad_i64_i32 v[22:23], s[8:9], v18, s39, v[22:23]
	s_lshl_b32 s14, s11, 1
	v_lshl_add_u64 v[22:23], v[22:23], 0, s[14:15]
	v_lshlrev_b32_e32 v18, 1, v32
	v_lshl_add_u64 v[22:23], v[22:23], 0, v[18:19]
	v_add_co_u32_e32 v22, vcc, 0x770000, v22
	s_waitcnt vmcnt(3)
	ds_write2_b32 v35, v0, v1 offset1:1
	ds_write2_b32 v36, v2, v3 offset1:1
	s_waitcnt vmcnt(2)
	ds_write2_b32 v37, v4, v5 offset1:1
	ds_write2_b32 v33, v6, v7 offset1:1
	s_waitcnt lgkmcnt(0)
	s_barrier
	ds_read2_b32 v[0:1], v38 offset1:65
	ds_read2_b32 v[2:3], v38 offset0:130 offset1:195
	ds_read2_b32 v[4:5], v34 offset0:4 offset1:69
	ds_read2_b32 v[6:7], v34 offset0:134 offset1:199
	v_addc_co_u32_e32 v23, vcc, 0, v23, vcc
	s_waitcnt lgkmcnt(3)
	v_cvt_pk_bf16_f32 v0, v0, v1
	s_waitcnt lgkmcnt(2)
	v_cvt_pk_bf16_f32 v1, v2, v3
	s_waitcnt lgkmcnt(1)
	v_cvt_pk_bf16_f32 v2, v4, v5
	s_waitcnt lgkmcnt(0)
	v_cvt_pk_bf16_f32 v3, v6, v7
	global_store_dwordx4 v[22:23], v[0:3], off
	s_barrier
